# attention prefill/decode loops: removed 43 canonicalizing v_max x,x ops (no-ops on finite values) on top of v48
# speedup vs baseline: 1.0188x; 1.0024x over previous
.LBB0_886:
	ds_read_b128 v[180:183], v207 offset:0
	ds_read_b128 v[184:187], v207 offset:64
	ds_read_b128 v[188:191], v207 offset:0x80
	ds_read_b128 v[212:215], v207 offset:0xc0
	ds_read_b128 v[216:219], v207 offset:0x100
	ds_read_b128 v[230:233], v207 offset:0x140
	ds_read_b128 v[234:237], v207 offset:0x180
	ds_read_b128 v[238:241], v207 offset:0x1c0
	ds_read_b128 v[242:245], v207 offset:0x200
	ds_read_b128 v[246:249], v207 offset:0x240
	s_nop 0
	s_waitcnt lgkmcnt(5)
	s_cmpk_eq_i32 s62, 0x80
	s_waitcnt lgkmcnt(14)
	v_mfma_f32_16x16x32_bf16 v[180:183], v[180:183], v[12:15], 0
	s_waitcnt lgkmcnt(0)
	s_cselect_b64 vcc, -1, 0
	v_mfma_f32_16x16x32_bf16 v[180:183], v[184:187], v[16:19], v[180:183]
	v_mfma_f32_16x16x32_bf16 v[180:183], v[188:191], v[20:23], v[180:183]
	v_mfma_f32_16x16x32_bf16 v[180:183], v[212:215], v[24:27], v[180:183]
	v_mfma_f32_16x16x32_bf16 v[180:183], v[216:219], v[28:31], v[180:183]
	s_waitcnt lgkmcnt(13)
	v_mfma_f32_16x16x32_bf16 v[180:183], v[230:233], v[32:35], v[180:183]
	s_waitcnt lgkmcnt(12)
	v_mfma_f32_16x16x32_bf16 v[180:183], v[234:237], v[36:39], v[180:183]
	s_waitcnt lgkmcnt(11)
	v_mfma_f32_16x16x32_bf16 v[180:183], v[238:241], v[40:43], v[180:183]
	s_waitcnt lgkmcnt(10)
	v_mfma_f32_16x16x32_bf16 v[180:183], v[242:245], v[44:47], v[180:183]
	s_waitcnt lgkmcnt(9)
	v_mfma_f32_16x16x32_bf16 v[180:183], v[246:249], v[48:51], v[180:183]
	s_nop 7
	v_cndmask_b32_e64 v0, v225, v180, s[8:9]
	v_cndmask_b32_e32 v195, v180, v0, vcc
	v_cndmask_b32_e32 v1, v182, v225, vcc
	v_cndmask_b32_e32 v0, v183, v225, vcc
	v_cndmask_b32_e32 v3, v181, v225, vcc
	v_max_f32_e32 v180, v1, v0
	v_max3_f32 v180, v195, v3, v180
	v_mov_b32_e32 v181, v180
	s_nop 1
	v_permlane16_swap_b32_e32 v180, v181
	v_max_f32_e32 v180, v180, v181
	v_mov_b32_e32 v181, v180
	s_nop 1
	v_permlane32_swap_b32_e32 v180, v181
	v_max_f32_e32 v211, v180, v181
	v_cmp_gt_f32_e32 vcc, v211, v156
	s_cbranch_vccz .LBB0_888
	v_max_f32_e32 v181, v156, v156
	v_max_f32_e32 v180, v181, v211
	v_sub_f32_e32 v156, v156, v180
	v_mul_f32_e32 v156, 0x3dd53b94, v156
	v_exp_f32_e32 v156, v156
	s_nop 0
	v_pk_mul_f32 v[74:75], v[74:75], v[156:157] op_sel_hi:[1,0]
	v_pk_mul_f32 v[72:73], v[72:73], v[156:157] op_sel_hi:[1,0]
	v_pk_mul_f32 v[70:71], v[70:71], v[156:157] op_sel_hi:[1,0]
	v_pk_mul_f32 v[68:69], v[68:69], v[156:157] op_sel_hi:[1,0]
	v_pk_mul_f32 v[66:67], v[66:67], v[156:157] op_sel_hi:[1,0]
	v_pk_mul_f32 v[64:65], v[64:65], v[156:157] op_sel_hi:[1,0]
	v_pk_mul_f32 v[62:63], v[62:63], v[156:157] op_sel_hi:[1,0]
	v_pk_mul_f32 v[60:61], v[60:61], v[156:157] op_sel_hi:[1,0]
	v_pk_mul_f32 v[58:59], v[58:59], v[156:157] op_sel_hi:[1,0]
	v_pk_mul_f32 v[56:57], v[56:57], v[156:157] op_sel_hi:[1,0]
	v_pk_mul_f32 v[54:55], v[54:55], v[156:157] op_sel_hi:[1,0]
	v_pk_mul_f32 v[52:53], v[52:53], v[156:157] op_sel_hi:[1,0]
	v_pk_mul_f32 v[10:11], v[10:11], v[156:157] op_sel_hi:[1,0]
	v_pk_mul_f32 v[8:9], v[8:9], v[156:157] op_sel_hi:[1,0]
	v_pk_mul_f32 v[6:7], v[6:7], v[156:157] op_sel_hi:[1,0]
	v_pk_mul_f32 v[4:5], v[4:5], v[156:157] op_sel_hi:[1,0]
	v_mul_f32_e32 v157, v157, v156
	v_mov_b32_e32 v156, v180

.LBB0_899:
	ds_read_b128 v[180:183], v209 offset:0
	ds_read_b128 v[184:187], v209 offset:64
	ds_read_b128 v[188:191], v209 offset:0x80
	ds_read_b128 v[212:215], v209 offset:0xc0
	ds_read_b128 v[216:219], v209 offset:0x100
	ds_read_b128 v[230:233], v209 offset:0x140
	ds_read_b128 v[234:237], v209 offset:0x180
	ds_read_b128 v[238:241], v209 offset:0x1c0
	ds_read_b128 v[242:245], v209 offset:0x200
	ds_read_b128 v[246:249], v209 offset:0x240
	s_nop 0
	s_waitcnt lgkmcnt(5)
	s_cmpk_eq_i32 s62, 0x7f
	v_mfma_f32_16x16x32_bf16 v[180:183], v[180:183], v[12:15], 0
	s_waitcnt lgkmcnt(0)
	s_cselect_b64 vcc, -1, 0
	v_mfma_f32_16x16x32_bf16 v[180:183], v[184:187], v[16:19], v[180:183]
	v_mfma_f32_16x16x32_bf16 v[180:183], v[188:191], v[20:23], v[180:183]
	v_mfma_f32_16x16x32_bf16 v[180:183], v[212:215], v[24:27], v[180:183]
	v_mfma_f32_16x16x32_bf16 v[180:183], v[216:219], v[28:31], v[180:183]
	v_mfma_f32_16x16x32_bf16 v[180:183], v[230:233], v[32:35], v[180:183]
	v_mfma_f32_16x16x32_bf16 v[180:183], v[234:237], v[36:39], v[180:183]
	v_mfma_f32_16x16x32_bf16 v[180:183], v[238:241], v[40:43], v[180:183]
	v_mfma_f32_16x16x32_bf16 v[180:183], v[242:245], v[44:47], v[180:183]
	v_mfma_f32_16x16x32_bf16 v[180:183], v[246:249], v[48:51], v[180:183]
	s_nop 7
	v_cndmask_b32_e64 v0, v225, v180, s[10:11]
	v_cndmask_b32_e32 v195, v180, v0, vcc
	v_cndmask_b32_e32 v1, v182, v225, vcc
	v_cndmask_b32_e32 v0, v183, v225, vcc
	v_cndmask_b32_e32 v3, v181, v225, vcc
	v_max_f32_e32 v180, v1, v0
	v_max3_f32 v180, v195, v3, v180
	v_mov_b32_e32 v181, v180
	s_nop 1
	v_permlane16_swap_b32_e32 v180, v181
	v_max_f32_e32 v180, v180, v181
	v_mov_b32_e32 v181, v180
	s_nop 1
	v_permlane32_swap_b32_e32 v180, v181
	v_max_f32_e32 v211, v180, v181
	v_cmp_gt_f32_e32 vcc, v211, v156
	s_cbranch_vccz .LBB0_901
	v_max_f32_e32 v181, v156, v156
	v_max_f32_e32 v180, v181, v211
	v_sub_f32_e32 v156, v156, v180
	v_mul_f32_e32 v156, 0x3dd53b94, v156
	v_exp_f32_e32 v156, v156
	s_nop 0
	v_pk_mul_f32 v[6:7], v[6:7], v[156:157] op_sel_hi:[1,0]
	v_pk_mul_f32 v[4:5], v[4:5], v[156:157] op_sel_hi:[1,0]
	v_pk_mul_f32 v[10:11], v[10:11], v[156:157] op_sel_hi:[1,0]
	v_pk_mul_f32 v[8:9], v[8:9], v[156:157] op_sel_hi:[1,0]
	v_pk_mul_f32 v[54:55], v[54:55], v[156:157] op_sel_hi:[1,0]
	v_pk_mul_f32 v[52:53], v[52:53], v[156:157] op_sel_hi:[1,0]
	v_pk_mul_f32 v[58:59], v[58:59], v[156:157] op_sel_hi:[1,0]
	v_pk_mul_f32 v[56:57], v[56:57], v[156:157] op_sel_hi:[1,0]
	v_pk_mul_f32 v[62:63], v[62:63], v[156:157] op_sel_hi:[1,0]
	v_pk_mul_f32 v[60:61], v[60:61], v[156:157] op_sel_hi:[1,0]
	v_pk_mul_f32 v[66:67], v[66:67], v[156:157] op_sel_hi:[1,0]
	v_pk_mul_f32 v[64:65], v[64:65], v[156:157] op_sel_hi:[1,0]
	v_pk_mul_f32 v[70:71], v[70:71], v[156:157] op_sel_hi:[1,0]
	v_pk_mul_f32 v[68:69], v[68:69], v[156:157] op_sel_hi:[1,0]
	v_pk_mul_f32 v[74:75], v[74:75], v[156:157] op_sel_hi:[1,0]
	v_pk_mul_f32 v[72:73], v[72:73], v[156:157] op_sel_hi:[1,0]
	v_mul_f32_e32 v157, v157, v156
	v_mov_b32_e32 v156, v180

.LBB0_941:
	v_max_f32_e32 v152, v158, v159
	v_max_f32_e32 v153, v240, v241
	v_max_f32_e32 v154, v244, v245
	v_max_f32_e32 v155, v246, v247
	v_max_f32_e32 v161, v243, v243
	v_max_f32_e32 v160, v161, v232
	v_max3_f32 v160, v1, v242, v160
	v_max3_f32 v152, v156, v157, v152
	v_max3_f32 v153, v238, v239, v153
	v_max3_f32 v154, v154, v155, v160
	v_max3_f32 v152, v152, v153, v154
	v_mov_b32_e32 v153, v152
	s_nop 1
	v_permlane16_swap_b32_e32 v152, v153
	v_max_f32_e32 v152, v152, v153
	v_mov_b32_e32 v153, v152
	s_nop 1
	v_permlane32_swap_b32_e32 v152, v153
	v_max_f32_e32 v152, v152, v153
	v_cmp_gt_f32_e32 vcc, v152, v0
	s_cbranch_vccz .LBB0_943
	v_max_f32_e32 v153, v0, v0
	v_max_f32_e32 v152, v153, v152
	v_sub_f32_e32 v0, v0, v152
	v_mul_f32_e32 v0, 0x3dd53b94, v0
	v_exp_f32_e32 v0, v0
	s_nop 0
	v_mul_f32_e32 v3, v3, v0
	v_pk_mul_f32 v[134:135], v[134:135], v[0:1] op_sel_hi:[1,0]
	v_pk_mul_f32 v[132:133], v[132:133], v[0:1] op_sel_hi:[1,0]
	v_pk_mul_f32 v[130:131], v[130:131], v[0:1] op_sel_hi:[1,0]
	v_pk_mul_f32 v[128:129], v[128:129], v[0:1] op_sel_hi:[1,0]
	v_pk_mul_f32 v[126:127], v[126:127], v[0:1] op_sel_hi:[1,0]
	v_pk_mul_f32 v[124:125], v[124:125], v[0:1] op_sel_hi:[1,0]
	v_pk_mul_f32 v[122:123], v[122:123], v[0:1] op_sel_hi:[1,0]
	v_pk_mul_f32 v[120:121], v[120:121], v[0:1] op_sel_hi:[1,0]
	v_pk_mul_f32 v[118:119], v[118:119], v[0:1] op_sel_hi:[1,0]
	v_pk_mul_f32 v[116:117], v[116:117], v[0:1] op_sel_hi:[1,0]
	v_pk_mul_f32 v[114:115], v[114:115], v[0:1] op_sel_hi:[1,0]
	v_pk_mul_f32 v[112:113], v[112:113], v[0:1] op_sel_hi:[1,0]
	v_pk_mul_f32 v[110:111], v[110:111], v[0:1] op_sel_hi:[1,0]
	v_pk_mul_f32 v[108:109], v[108:109], v[0:1] op_sel_hi:[1,0]
	v_pk_mul_f32 v[106:107], v[106:107], v[0:1] op_sel_hi:[1,0]
	v_pk_mul_f32 v[104:105], v[104:105], v[0:1] op_sel_hi:[1,0]
	v_mov_b32_e32 v0, v152

.LBB0_950:
	v_max_f32_e32 v136, v154, v155
	v_max_f32_e32 v137, v243, v242
	v_max_f32_e32 v138, v232, v170
	v_max_f32_e32 v139, v171, v169
	v_max_f32_e32 v141, v166, v166
	v_max_f32_e32 v140, v141, v165
	v_max3_f32 v140, v167, v168, v140
	v_max3_f32 v136, v152, v153, v136
	v_max3_f32 v137, v245, v244, v137
	v_max3_f32 v138, v138, v139, v140
	v_max3_f32 v136, v136, v137, v138
	v_mov_b32_e32 v137, v136
	s_nop 1
	v_permlane16_swap_b32_e32 v136, v137
	v_max_f32_e32 v136, v136, v137
	v_mov_b32_e32 v137, v136
	s_nop 1
	v_permlane32_swap_b32_e32 v136, v137
	v_max_f32_e32 v136, v136, v137
	v_cmp_gt_f32_e32 vcc, v136, v231
	s_cbranch_vccz .LBB0_952
	v_max_f32_e32 v137, v231, v136
	v_sub_f32_e32 v136, v231, v137
	v_mul_f32_e32 v136, 0x3dd53b94, v136
	v_exp_f32_e32 v136, v136
	v_mov_b32_e32 v231, v137
	v_mul_f32_e32 v209, v209, v136
	v_pk_mul_f32 v[102:103], v[102:103], v[136:137] op_sel_hi:[1,0]
	v_pk_mul_f32 v[100:101], v[100:101], v[136:137] op_sel_hi:[1,0]
	v_pk_mul_f32 v[98:99], v[98:99], v[136:137] op_sel_hi:[1,0]
	v_pk_mul_f32 v[96:97], v[96:97], v[136:137] op_sel_hi:[1,0]
	v_pk_mul_f32 v[94:95], v[94:95], v[136:137] op_sel_hi:[1,0]
	v_pk_mul_f32 v[92:93], v[92:93], v[136:137] op_sel_hi:[1,0]
	v_pk_mul_f32 v[90:91], v[90:91], v[136:137] op_sel_hi:[1,0]
	v_pk_mul_f32 v[88:89], v[88:89], v[136:137] op_sel_hi:[1,0]
	v_pk_mul_f32 v[86:87], v[86:87], v[136:137] op_sel_hi:[1,0]
	v_pk_mul_f32 v[84:85], v[84:85], v[136:137] op_sel_hi:[1,0]
	v_pk_mul_f32 v[82:83], v[82:83], v[136:137] op_sel_hi:[1,0]
	v_pk_mul_f32 v[80:81], v[80:81], v[136:137] op_sel_hi:[1,0]
	v_pk_mul_f32 v[78:79], v[78:79], v[136:137] op_sel_hi:[1,0]
	v_pk_mul_f32 v[76:77], v[76:77], v[136:137] op_sel_hi:[1,0]
	v_pk_mul_f32 v[74:75], v[74:75], v[136:137] op_sel_hi:[1,0]
	v_pk_mul_f32 v[72:73], v[72:73], v[136:137] op_sel_hi:[1,0]
